# attention: static s_setprio 1 for waves 4-7 during the attention phase (younger half), on top of v5b
# speedup vs baseline: 1.0165x; 1.0009x over previous
; #define LAS __attribute__((address_space(3)))
; __device__ __forceinline__ void attn_phase(const Ptrs& P, LAS unsigned char* lds, int vcu) {
;     const int tid = threadIdx.x, lane = tid & 63, wid = __builtin_amdgcn_readfirstlane(tid >> 6), r32 = lane & 31, hi = lane >> 5;
;     const bf16_t* QI = (const bf16_t*)(P.ws + WS_QIMG); const bf16_t* KN = (const bf16_t*)(P.ws + WS_RA); const bf16_t* KPE = (const bf16_t*)(P.ws + WS_KPE); const bf16_t* VI = (const bf16_t*)(P.ws + WS_VIMG);
;     bf16_t* A2 = (bf16_t*)(P.ws + WS_A2);
;     const int bh = vcu >> 1, b = bh >> 3, head = bh & 7;
;     const bf16_t* kn_b = KN + (size_t)bh * 64 * 4096 + lane * 8; const bf16_t* kpe_b = KPE + (size_t)b * 64 * 2048 + lane * 8; const bf16_t* v_b = VI + (size_t)bh * 256 * 1024 + lane * 8;
;     LAS unsigned char* const wz = lds + 2 * ATT_STAGE + wid * 8192;
;     const int vb = 24576 + (4 * hi + ((lane & 15) >> 2)) * 64 + ((lane >> 4) & 1) * 32 + (lane & 3) * 8;
.LBB0_1114:
	s_ashr_i32 s10, s87, 1
	s_ashr_i32 s12, s87, 4
	v_readfirstlane_b32 s16, v200
	s_ashr_i32 s11, s10, 31
	s_ashr_i32 s13, s12, 31
	s_lshr_b32 s17, s16, 6
	s_cmp_eq_u32 s17, 3
	s_cselect_b32 s32, 30, 0
	s_cmp_eq_u32 s17, 4
	s_cselect_b32 s32, 15, s32
	s_cmp_lt_u32 s17, 4
	s_cbranch_scc1 .Lattn_prio_skip
	s_setprio 1
.Lattn_prio_skip:
	s_lshl_b64 s[2:3], s[10:11], 19
	s_lshl_b64 s[0:1], s[12:13], 18
	s_cmpk_lt_u32 s16, 0x100
	s_cselect_b64 s[6:7], -1, 0
	s_cmpk_gt_u32 s16, 0xff
	s_cselect_b64 s[76:77], -1, 0
	v_lshl_add_u64 v[2:3], v[180:181], 0, s[0:1]
	v_lshl_add_u64 v[188:189], v[182:183], 0, s[2:3]
	s_mov_b64 s[4:5], -1
	s_and_b64 vcc, exec, s[76:77]
	s_mul_i32 s20, s17, 0xa00
	s_cbranch_vccz .LBB0_1120
	s_cmpk_gt_u32 s16, 0x13f
	s_cbranch_scc0 .LBB0_1117
	s_add_i32 s72, s20, 0xffffd000
	v_lshl_add_u64 v[4:5], s[72:73], 1, v[188:189]
	s_mov_b64 s[4:5], 0

; __device__ __forceinline__ void attn_phase(const Ptrs& P, LAS unsigned char* lds, int vcu) {
;     ...
;                 { constexpr int PD = 4;
;                   bf16x8 ka[12], kb[12];
; #pragma unroll
;                   for (int ks = 0; ks < PD; ++ks) { ka[ks] = lds_rd16(st + KOFF0(ks) + lane * 16); kb[ks] = lds_rd16(st + KOFF1(ks) + lane * 16); }
;                   __builtin_amdgcn_sched_barrier(0);
; #pragma unroll
;                   for (int ks = 0; ks < 12; ++ks) {
;                       if (ks + PD < 12) { ka[ks + PD] = lds_rd16(st + KOFF0(ks + PD) + lane * 16); kb[ks + PD] = lds_rd16(st + KOFF1(ks + PD) + lane * 16); }
;                       p0 = __builtin_amdgcn_mfma_f32_32x32x16_bf16(ka[ks], qf[ks], ks == 0 ? negmv : p0, 0, 0, 0);
;                       p1 = __builtin_amdgcn_mfma_f32_32x32x16_bf16(kb[ks], qf[ks], ks == 0 ? negmv : p1, 0, 0, 0);
;                       __builtin_amdgcn_sched_barrier(0);
;                   } }
.LBB0_1218:
	s_bitcmp1_b32 s8, 0
	s_cselect_b32 s0, 0xa000, 0
	s_add_i32 s70, s0, 0
	v_add_u32_e32 v0, s70, v176
	ds_read_b128 v[2:5], v0
	ds_read_b128 v[6:9], v0 offset:1024
	ds_read_b128 v[12:15], v0 offset:8192
	ds_read_b128 v[226:229], v0 offset:9216
	ds_read_b128 v[230:233], v0 offset:2048
	ds_read_b128 v[234:237], v0 offset:3072
	ds_read_b128 v[238:241], v0 offset:10240
	ds_read_b128 v[242:245], v0 offset:11264
	s_waitcnt lgkmcnt(0)
	v_mfma_f32_32x32x16_bf16 v[112:127], v[2:5], v[128:131], v[80:95]
	ds_read_b128 v[2:5], v0 offset:4096
	ds_read_b128 v[246:249], v0 offset:12288
	v_mfma_f32_32x32x16_bf16 v[96:111], v[12:15], v[128:131], v[80:95]
	v_mfma_f32_32x32x16_bf16 v[112:127], v[6:9], v[132:135], v[112:127]
	ds_read_b128 v[6:9], v0 offset:5120
	ds_read_b128 v[12:15], v0 offset:13312
	v_mfma_f32_32x32x16_bf16 v[96:111], v[226:229], v[132:135], v[96:111]
	v_mfma_f32_32x32x16_bf16 v[112:127], v[230:233], v[136:139], v[112:127]
	ds_read_b128 v[226:229], v0 offset:6144
	ds_read_b128 v[230:233], v0 offset:14336
	v_mfma_f32_32x32x16_bf16 v[96:111], v[238:241], v[136:139], v[96:111]
	v_mfma_f32_32x32x16_bf16 v[112:127], v[234:237], v[140:143], v[112:127]
	ds_read_b128 v[234:237], v0 offset:7168
	ds_read_b128 v[238:241], v0 offset:15360
	v_mfma_f32_32x32x16_bf16 v[96:111], v[242:245], v[140:143], v[96:111]
	s_waitcnt lgkmcnt(0)
	v_mfma_f32_32x32x16_bf16 v[112:127], v[2:5], v[148:151], v[112:127]
	ds_read_b128 v[2:5], v0 offset:16384
	ds_read_b128 v[242:245], v0 offset:20480
	v_mfma_f32_32x32x16_bf16 v[96:111], v[246:249], v[148:151], v[96:111]
	v_mfma_f32_32x32x16_bf16 v[112:127], v[6:9], v[144:147], v[112:127]
	ds_read_b128 v[6:9], v0 offset:17408
	ds_read_b128 v[246:249], v0 offset:21504
	v_mfma_f32_32x32x16_bf16 v[96:111], v[12:15], v[144:147], v[96:111]
	v_mfma_f32_32x32x16_bf16 v[112:127], v[226:229], v[152:155], v[112:127]
	ds_read_b128 v[12:15], v0 offset:18432
	ds_read_b128 v[226:229], v0 offset:22528
	v_mfma_f32_32x32x16_bf16 v[96:111], v[230:233], v[152:155], v[96:111]
	v_mfma_f32_32x32x16_bf16 v[112:127], v[234:237], v[156:159], v[112:127]
	ds_read_b128 v[230:233], v0 offset:19456
	ds_read_b128 v[234:237], v0 offset:23552
	v_mfma_f32_32x32x16_bf16 v[96:111], v[238:241], v[156:159], v[96:111]
	s_waitcnt lgkmcnt(0)
	v_mfma_f32_32x32x16_bf16 v[112:127], v[2:5], v[160:163], v[112:127]
	v_mfma_f32_32x32x16_bf16 v[96:111], v[242:245], v[160:163], v[96:111]
	v_mfma_f32_32x32x16_bf16 v[112:127], v[6:9], v[164:167], v[112:127]
	v_mfma_f32_32x32x16_bf16 v[96:111], v[246:249], v[164:167], v[96:111]
	v_mfma_f32_32x32x16_bf16 v[112:127], v[12:15], v[168:171], v[112:127]
	v_mfma_f32_32x32x16_bf16 v[96:111], v[226:229], v[168:171], v[96:111]
	v_mfma_f32_32x32x16_bf16 v[112:127], v[230:233], v[172:175], v[112:127]
	v_mfma_f32_32x32x16_bf16 v[96:111], v[234:237], v[172:175], v[96:111]
	s_cmp_le_u32 s90, s92
	s_cbranch_scc1 .LBB0_1220
; __device__ __forceinline__ float max3f_(float a, float b, float c) { float r; asm("v_max3_f32 %0, %1, %2, %3" : "=v"(r) : "v"(a), "v"(b), "v"(c)); return r; }
; __device__ __forceinline__ void attn_phase(const Ptrs& P, LAS unsigned char* lds, int vcu) {
;     ...
;                 if (64 * t + 63 > qw) {
;                     const int qa = qw + r32 - 64 * t - 4 * hi;
; #pragma unroll
;                     for (int i = 0; i < 16; ++i) { const int kv = (i & 3) + 8 * (i >> 2); if (kv > qa) p0[i] = -INFINITY; if (kv + 32 > qa) p1[i] = -INFINITY; }
;                 }
;                 float rm = max3f_(p0[0], p1[0], p0[1]);
;                 rm = max3f_(rm, p1[1], p0[2]);
; #pragma unroll
;                 for (int i = 2; i < 15; ++i) rm = max3f_(rm, p1[i], p0[i + 1]);
;                 rm = fmaxf(rm, p1[15]);
;                 { auto rr = __builtin_amdgcn_permlane32_swap(__float_as_uint(rm), __float_as_uint(rm), false, false); rm = fmaxf(__uint_as_float(rr[0]), __uint_as_float(rr[1])); }
	v_cmp_gt_i32_e64 s[64:65], 26, v223
	v_cmp_gt_i32_e64 s[66:67], 27, v223
	v_cmp_gt_i32_e64 s[62:63], 25, v223
	s_and_b64 s[64:65], s[66:67], s[64:65]
	v_cmp_gt_i32_e64 s[60:61], 24, v223
	s_and_b64 s[62:63], s[64:65], s[62:63]
	v_cmp_gt_i32_e64 s[58:59], 19, v223
	s_and_b64 s[60:61], s[62:63], s[60:61]
	v_cmp_gt_i32_e64 s[56:57], 18, v223
	s_and_b64 s[58:59], s[60:61], s[58:59]
	v_cmp_gt_i32_e64 s[54:55], 17, v223
	s_and_b64 s[56:57], s[58:59], s[56:57]
	v_cmp_gt_i32_e64 s[52:53], 16, v223
	s_and_b64 s[54:55], s[56:57], s[54:55]
	v_cmp_gt_i32_e64 s[50:51], 11, v223
	s_and_b64 s[52:53], s[54:55], s[52:53]
	v_cmp_gt_i32_e64 s[48:49], 10, v223
	s_and_b64 s[50:51], s[52:53], s[50:51]
	v_cmp_gt_i32_e64 s[46:47], 9, v223
	s_and_b64 s[48:49], s[50:51], s[48:49]
	v_cmp_gt_i32_e64 s[44:45], 8, v223
	s_and_b64 s[46:47], s[48:49], s[46:47]
	v_cmp_gt_i32_e64 s[42:43], 3, v223
	s_and_b64 s[44:45], s[46:47], s[44:45]
	v_cmp_gt_i32_e64 s[40:41], 2, v223
	s_and_b64 s[42:43], s[44:45], s[42:43]
	v_cmp_gt_i32_e64 s[38:39], 1, v223
	s_and_b64 s[40:41], s[42:43], s[40:41]
	v_cmp_gt_i32_e64 s[36:37], 0, v223
	s_and_b64 s[38:39], s[40:41], s[38:39]
	s_and_b64 s[36:37], s[38:39], s[36:37]
	v_cmp_gt_i32_e64 s[34:35], 58, v223
	v_cndmask_b32_e64 v112, v112, v220, s[36:37]
	v_cmp_gt_i32_e64 s[36:37], 59, v223
	v_cmp_gt_i32_e64 s[30:31], 57, v223
	s_and_b64 s[34:35], s[36:37], s[34:35]
	v_cmp_gt_i32_e64 s[28:29], 56, v223
	s_and_b64 s[30:31], s[34:35], s[30:31]
	v_cmp_gt_i32_e64 s[26:27], 51, v223
	s_and_b64 s[28:29], s[30:31], s[28:29]
	v_cmp_gt_i32_e64 s[24:25], 50, v223
	s_and_b64 s[26:27], s[28:29], s[26:27]
	v_cmp_gt_i32_e64 s[22:23], 49, v223
	s_and_b64 s[24:25], s[26:27], s[24:25]
	v_cmp_gt_i32_e64 s[20:21], 48, v223
	s_and_b64 s[22:23], s[24:25], s[22:23]
	v_cmp_gt_i32_e64 s[18:19], 43, v223
	s_and_b64 s[20:21], s[22:23], s[20:21]
	v_cmp_gt_i32_e64 s[16:17], 42, v223
	s_and_b64 s[18:19], s[20:21], s[18:19]
	v_cmp_gt_i32_e64 s[14:15], 41, v223
	s_and_b64 s[16:17], s[18:19], s[16:17]
	v_cmp_gt_i32_e64 s[12:13], 40, v223
	s_and_b64 s[14:15], s[16:17], s[14:15]
	v_cmp_gt_i32_e64 s[8:9], 35, v223
	s_and_b64 s[12:13], s[14:15], s[12:13]
	v_cmp_gt_i32_e64 s[6:7], 34, v223
	s_and_b64 s[8:9], s[12:13], s[8:9]
	v_cmp_gt_i32_e64 s[0:1], 33, v223
	s_and_b64 s[6:7], s[8:9], s[6:7]
	v_cmp_gt_i32_e32 vcc, 32, v223
	s_and_b64 s[0:1], s[6:7], s[0:1]
	v_cndmask_b32_e64 v125, v125, v220, s[62:63]
	v_cndmask_b32_e64 v124, v124, v220, s[60:61]
	v_cndmask_b32_e64 v123, v123, v220, s[58:59]
	v_cndmask_b32_e64 v122, v122, v220, s[56:57]
	v_cndmask_b32_e64 v121, v121, v220, s[54:55]
	v_cndmask_b32_e64 v120, v120, v220, s[52:53]
	v_cndmask_b32_e64 v119, v119, v220, s[50:51]
	v_cndmask_b32_e64 v118, v118, v220, s[48:49]
	v_readlane_b32 s48, v254, 23
	s_and_b64 vcc, s[0:1], vcc
	v_cndmask_b32_e64 v127, v127, v220, s[66:67]
	v_cndmask_b32_e64 v126, v126, v220, s[64:65]
	v_readlane_b32 s49, v254, 24
	v_cndmask_b32_e64 v117, v117, v220, s[46:47]
	v_cndmask_b32_e64 v116, v116, v220, s[44:45]
	v_cndmask_b32_e64 v115, v115, v220, s[42:43]
	v_cndmask_b32_e64 v114, v114, v220, s[40:41]
	v_cndmask_b32_e64 v113, v113, v220, s[38:39]
	v_cndmask_b32_e64 v111, v111, v220, s[36:37]
	v_cndmask_b32_e64 v110, v110, v220, s[34:35]
	v_cndmask_b32_e64 v109, v109, v220, s[30:31]
	v_cndmask_b32_e64 v108, v108, v220, s[28:29]
	v_cndmask_b32_e64 v107, v107, v220, s[26:27]
	v_cndmask_b32_e64 v106, v106, v220, s[24:25]
	v_cndmask_b32_e64 v105, v105, v220, s[22:23]
	v_cndmask_b32_e64 v104, v104, v220, s[20:21]
	v_cndmask_b32_e64 v103, v103, v220, s[18:19]
	v_cndmask_b32_e64 v102, v102, v220, s[16:17]
	v_cndmask_b32_e64 v101, v101, v220, s[14:15]
	v_cndmask_b32_e64 v100, v100, v220, s[12:13]
	v_cndmask_b32_e64 v99, v99, v220, s[8:9]
	v_cndmask_b32_e64 v98, v98, v220, s[6:7]
	v_cndmask_b32_e64 v97, v97, v220, s[0:1]
	v_cndmask_b32_e32 v96, v96, v220, vcc
	v_readlane_b32 s50, v254, 25
	v_readlane_b32 s51, v254, 26
	v_readlane_b32 s52, v254, 27
	v_readlane_b32 s53, v254, 28
	v_readlane_b32 s54, v254, 29
	v_readlane_b32 s55, v254, 30
	v_readlane_b32 s56, v254, 31
	v_readlane_b32 s57, v254, 32
	v_readlane_b32 s58, v254, 33
	v_readlane_b32 s59, v254, 34
	v_readlane_b32 s60, v254, 35
	v_readlane_b32 s61, v254, 36
	v_readlane_b32 s62, v254, 37
	v_readlane_b32 s63, v254, 38
.LBB0_1220:
	v_max3_f32 v0, v112, v96, v113
	s_nop 9
	v_max_f32_e32 v2, v111, v111
	v_max3_f32 v0, v0, v97, v114
	s_cmp_lg_u32 s82, 0
	v_max3_f32 v0, v0, v98, v115
	s_cselect_b64 s[0:1], -1, 0
	v_max3_f32 v0, v0, v99, v116
	s_cmp_eq_u32 s82, 0
	v_max3_f32 v0, v0, v100, v117
	v_max3_f32 v0, v0, v101, v118
	v_max3_f32 v0, v0, v102, v119
	v_max3_f32 v0, v0, v103, v120
	v_max3_f32 v0, v0, v104, v121
	v_max3_f32 v0, v0, v105, v122
	v_max3_f32 v0, v0, v106, v123
	v_max3_f32 v0, v0, v107, v124
	v_max3_f32 v0, v0, v108, v125
	v_max3_f32 v0, v0, v109, v126
	v_max3_f32 v0, v0, v110, v127
	s_nop 0
	v_max_f32_e32 v0, v0, v0
	v_max_f32_e32 v0, v0, v2
	v_mov_b32_e32 v2, v0
	s_nop 1
	v_permlane32_swap_b32_e32 v0, v2
	v_max_f32_e32 v2, v2, v2
	v_max_f32_e32 v0, v0, v0
	v_max_f32_e32 v0, v0, v2
	s_cbranch_scc1 .LBB0_1223
	s_mov_b32 s6, 0x41000000
	v_cmp_lt_f32_e32 vcc, s6, v0
	s_cbranch_vccz .LBB0_1224
	v_max_f32_e32 v0, v0, v0
	v_max_f32_e32 v0, 0, v0
	v_mov_b32_e32 v2, v224
	s_cbranch_execnz .LBB0_1225
	s_branch .LBB0_1228

; #define SEAM(k) do { if (IN(k) && IN((k) + 1)) { xcd_barrier(bar); } } while (0)
; __device__ __forceinline__ void attn_phase(const Ptrs& P, LAS unsigned char* lds, int vcu) {
;     ...
;     asm volatile("s_waitcnt vmcnt(0)" ::: "memory");
;     __syncthreads();
; __global__ void __launch_bounds__(512, 2) fwd_kernel(Args a) {
;     ...
;     if (IN(4)) { for (int v = vcu; v < 256; v += G) attn_phase(P, lds, v); } SEAM(4);
.LBB0_1233:
	s_setprio 0
	v_readlane_b32 s92, v254, 41
	v_readlane_b32 s2, v254, 39
	v_readlane_b32 s80, v254, 43
	v_readlane_b32 s93, v254, 42
	v_readlane_b32 s3, v254, 40

; template <class Epi, class Sched, bool ALIGN_EPI = false, bool SP2 = false>
; __device__ __forceinline__ void gemm_phase(PG8_LAS unsigned char* lds, const Gemm g, const Sched& S, const Epi& E) {
;     ...
;     f32x4 acc[2][2][4][2];
; #pragma unroll
;     for (int a = 0; a < 2; ++a)
; #pragma unroll
;         for (int b = 0; b < 2; ++b)
; #pragma unroll
;             for (int m = 0; m < 4; ++m)
; #pragma unroll
;                 for (int n = 0; n < 2; ++n) acc[a][b][m][n] = (f32x4){0.f, 0.f, 0.f, 0.f};
;     ...
;         for (int a = 0; a < 2; ++a)
; #pragma unroll
;             for (int b = 0; b < 2; ++b)
; #pragma unroll
;                 for (int m = 0; m < 4; ++m)
; #pragma unroll
;                     for (int n = 0; n < 2; ++n) acc[a][b][m][n] = (f32x4){0.f, 0.f, 0.f, 0.f};
.LBB0_1309:
	s_waitcnt vmcnt(0)
	s_andn2_b64 vcc, exec, s[14:15]
	s_cbranch_vccnz .LBB0_1314
	s_lshl_b32 s22, s57, 8
	s_lshl_b32 s58, s56, 8
	s_ashr_i32 s23, s22, 31
	s_add_i32 s58, s58, s43
	s_lshl_b64 s[22:23], s[22:23], 1
	s_add_u32 s22, s44, s22
	s_addc_u32 s23, s45, s23
	v_mov_b32_e32 v2, v0
	v_mov_b32_e32 v3, v0
	s_add_u32 s59, s24, 0x100
	v_mov_b32_e32 v1, v0
	v_mov_b64_e32 v[6:7], v[2:3]
	v_mov_b64_e32 v[10:11], v[2:3]
	v_mov_b64_e32 v[22:23], v[2:3]
	v_mov_b64_e32 v[26:27], v[2:3]
	v_mov_b64_e32 v[38:39], v[2:3]
	v_mov_b64_e32 v[42:43], v[2:3]
	v_mov_b64_e32 v[54:55], v[2:3]
	v_mov_b64_e32 v[58:59], v[2:3]
	v_mov_b64_e32 v[14:15], v[2:3]
	v_mov_b64_e32 v[18:19], v[2:3]
	v_mov_b64_e32 v[30:31], v[2:3]
	v_mov_b64_e32 v[34:35], v[2:3]
	v_mov_b64_e32 v[46:47], v[2:3]
	v_mov_b64_e32 v[50:51], v[2:3]
	v_mov_b64_e32 v[62:63], v[2:3]
	v_mov_b64_e32 v[66:67], v[2:3]
	v_mov_b64_e32 v[70:71], v[2:3]
	v_mov_b64_e32 v[74:75], v[2:3]
	v_mov_b64_e32 v[86:87], v[2:3]
	v_mov_b64_e32 v[90:91], v[2:3]
	v_mov_b64_e32 v[102:103], v[2:3]
	v_mov_b64_e32 v[106:107], v[2:3]
	v_mov_b64_e32 v[126:127], v[2:3]
	v_mov_b64_e32 v[130:131], v[2:3]
	v_mov_b64_e32 v[78:79], v[2:3]
	v_mov_b64_e32 v[82:83], v[2:3]
	v_mov_b64_e32 v[94:95], v[2:3]
	v_mov_b64_e32 v[98:99], v[2:3]
	v_mov_b64_e32 v[110:111], v[2:3]
	v_mov_b64_e32 v[114:115], v[2:3]
	v_mov_b64_e32 v[122:123], v[2:3]
	v_mov_b64_e32 v[118:119], v[2:3]
	s_addc_u32 s60, s25, 0
	v_lshl_add_u64 v[168:169], s[20:21], 0, v[180:181]
	v_lshl_add_u64 v[170:171], s[20:21], 0, v[182:183]
	s_mov_b32 s26, 0
	s_mov_b64 s[24:25], 0
	v_mov_b64_e32 v[4:5], v[0:1]
	v_mov_b64_e32 v[8:9], v[0:1]
	v_mov_b64_e32 v[20:21], v[0:1]
	v_mov_b64_e32 v[24:25], v[0:1]
	v_mov_b64_e32 v[36:37], v[0:1]
	v_mov_b64_e32 v[40:41], v[0:1]
	v_mov_b64_e32 v[52:53], v[0:1]
	v_mov_b64_e32 v[56:57], v[0:1]
	v_mov_b64_e32 v[12:13], v[0:1]
	v_mov_b64_e32 v[16:17], v[0:1]
	v_mov_b64_e32 v[28:29], v[0:1]
	v_mov_b64_e32 v[32:33], v[0:1]
	v_mov_b64_e32 v[44:45], v[0:1]
	v_mov_b64_e32 v[48:49], v[0:1]
	v_mov_b64_e32 v[60:61], v[0:1]
	v_mov_b64_e32 v[64:65], v[0:1]
	v_mov_b64_e32 v[68:69], v[0:1]
	v_mov_b64_e32 v[72:73], v[0:1]
	v_mov_b64_e32 v[84:85], v[0:1]
	v_mov_b64_e32 v[88:89], v[0:1]
	v_mov_b64_e32 v[100:101], v[0:1]
	v_mov_b64_e32 v[104:105], v[0:1]
	v_mov_b64_e32 v[124:125], v[0:1]
	v_mov_b64_e32 v[128:129], v[0:1]
	v_mov_b64_e32 v[76:77], v[0:1]
	v_mov_b64_e32 v[80:81], v[0:1]
	v_mov_b64_e32 v[92:93], v[0:1]
	v_mov_b64_e32 v[96:97], v[0:1]
	v_mov_b64_e32 v[108:109], v[0:1]
	v_mov_b64_e32 v[112:113], v[0:1]
	v_mov_b64_e32 v[120:121], v[0:1]
	v_mov_b64_e32 v[116:117], v[0:1]
	s_cmp_lg_u32 s26, 16
	s_cbranch_scc1 .LBB0_1312
